# k17 plus: first K-tile of each unit peeled in the two gate-up GEMMs (first-touch MFMAs take C=0), accumulator zeroing removed there
# speedup vs baseline: 1.0050x; 1.0050x over previous
;     __device__ bool next(int i, Unit& u) const { const bool r = base.next(i >> 1, u); u.kh = i & 1; return r; }
; #define PG8_STAGE(bufoff, gbase, voff) do { _Pragma("unroll") for (int _i = 0; _i < 2; ++_i) \
;         { unsigned _vo = (voff)[_i]; asm volatile("" : "+v"(_vo));     \
;         __builtin_amdgcn_global_load_lds((const unsigned*)((const char*)(gbase) + _vo), (PG8_LAS unsigned*)(lds + (bufoff) + ldsw + _i * 8192), 16, 0, 0); } } while (0)
; #define PG8_LDA(dst, b, h) do { _Pragma("unroll") for (int m = 0; m < 4; ++m) _Pragma("unroll") for (int k = 0; k < 2; ++k) dst[m][k] = *(const PG8_LAS bf16x8*)(lds + PG8_SA(b, h) + aoff + m * 2048 + k * 1024); } while (0)
; #define PG8_LDB(dst, b, h) do { _Pragma("unroll") for (int n = 0; n < 2; ++n) _Pragma("unroll") for (int k = 0; k < 2; ++k) dst[n][k] = *(const PG8_LAS bf16x8*)(lds + PG8_SB(b, h) + boff + n * 2048 + k * 1024); } while (0)
; #define PG8_WAIT_V(n) asm volatile("s_waitcnt vmcnt(" #n ")" ::: "memory")
; #define PG8_WAIT_L(n) asm volatile("s_waitcnt lgkmcnt(" #n ")" ::: "memory")
; #define PG8_BAR __builtin_amdgcn_s_barrier()
; template <class Epi, class Sched, bool ALIGN_EPI = false, bool SP2 = false, bool ABLK = false, bool F8 = false>
; __device__ __forceinline__ void gemm_phase(PG8_LAS unsigned char* lds, const Gemm g, const Sched& S, const Epi& E, const int wave_s) {
;     ...
;         const bool has_next = S.next(ui + 1, nxt); nxt.par = (ui + 1) & 1;
;         const char* nA = has_next ? (const char*)g.A + (size_t)nxt.pm * tstep + nxt.kh * khbA : cA; const char* nB = has_next ? (const char*)g.Bt + (size_t)nxt.pn * tstep + nxt.kh * khb : cB;
;         for (int t = 0; t < nt; t += 2) {
;             const bool last = (t == nt - 2);
;             const char* a1 = cA + (size_t)(t + 1) * kstepA;
;             const char* a2 = last ? nA : cA + (size_t)(t + 2) * kstepA; const char* b2 = last ? nB : cB + (size_t)(t + 2) * kstep;
;             const char* a3 = a2 + kstepA; const char* b3 = b2 + kstep;
;             if (last && has_next) { S.a_ready(nxt); if constexpr (Epi::PREF) E.prefetch(nxt, wid, lane); }
;             if constexpr (SP2) {
;             PG8_LDB(B0, 0, 0); PG8_LDB(B1, 0, 1); PG8_SCHED; PG8_LDA(At, 0, 0); PG8_STAGE(PG8_SA(1, 1), a1 + hstepA, voffA);
;             PG8_WAIT_V(8); PG8_WAIT_L(0); PG8_BAR; PG8_MMA(0, 0, At, B0); PG8_MMA(0, 1, At, B1); PG8_BAR; PG8_SCHED;
.LBB0_222:
	s_ashr_i32 s49, s48, 31
	s_and_b32 s67, s66, 1
	s_lshl_b64 s[50:51], s[48:49], 20
	s_add_u32 s50, s28, s50
	s_addc_u32 s51, s29, s51
	s_and_b64 s[52:53], exec, s[8:9]
	s_cselect_b32 s49, s59, s51
	s_cselect_b32 s77, s58, s50
	s_ashr_i32 s17, s16, 31
	s_lshl_b64 s[52:53], s[16:17], 20
	s_add_u32 s52, s18, s52
	s_addc_u32 s53, s21, s53
	s_and_b64 s[62:63], exec, s[8:9]
	s_cselect_b32 s17, s61, s53
	s_cselect_b32 s78, s60, s52
	s_lshl_b32 s62, s48, 8
	s_ashr_i32 s63, s62, 31
	s_lshl_b32 s72, s67, 10
	s_or_b64 s[8:9], s[44:45], s[8:9]
	s_add_u32 s58, s58, 0x80080
	s_addc_u32 s59, s59, 0
	s_add_u32 s79, s60, 0x100
	s_addc_u32 s80, s61, 0
	s_mov_b32 s81, -2
	s_add_i32 s82, s95, s72
	v_lshl_add_u64 v[154:155], s[62:63], 2, v[146:147]
	s_mov_b64 s[60:61], -1
	v_add_u32_e32 v128, s64, v160
	ds_read_b128 v[166:169], v128
	ds_read_b128 v[170:173], v128 offset:1024
	ds_read_b128 v[174:177], v128 offset:2048
	ds_read_b128 v[178:181], v128 offset:3072
	v_add_u32_e32 v128, s65, v160
	ds_read_b128 v[182:185], v128
	ds_read_b128 v[186:189], v128 offset:1024
	ds_read_b128 v[190:193], v128 offset:2048
	ds_read_b128 v[194:197], v128 offset:3072
	s_add_u32 s62, s58, 0xfff80080
	s_addc_u32 s63, s59, -1
	s_and_b64 s[60:61], s[60:61], exec
	s_cselect_b32 s61, s63, s49
	s_cselect_b32 s60, s62, s77
	s_cselect_b32 s63, s80, s17
	s_cselect_b32 s62, s79, s78
	ds_read_b128 v[198:201], v163
	ds_read_b128 v[202:205], v163 offset:1024
	ds_read_b128 v[206:209], v163 offset:2048
	ds_read_b128 v[210:213], v163 offset:3072
	ds_read_b128 v[214:217], v163 offset:4096
	ds_read_b128 v[218:221], v163 offset:5120
	ds_read_b128 v[222:225], v163 offset:6144
	ds_read_b128 v[230:233], v163 offset:7168
	s_add_i32 m0, s22, 0xc000
	s_nop 0
	global_load_lds_dwordx4 v156, s[58:59]
	s_add_i32 m0, s22, 0xe000
	s_nop 0
	global_load_lds_dwordx4 v158, s[58:59]
	s_waitcnt vmcnt(8)
	s_waitcnt lgkmcnt(0)
	s_barrier
	s_setprio 1
	s_waitcnt lgkmcnt(0)
	v_mfma_f32_16x16x32_bf16 v[124:127], v[166:169], v[198:201], 0
	v_mfma_f32_16x16x32_bf16 v[116:119], v[174:177], v[198:201], 0
	v_mfma_f32_16x16x32_bf16 v[108:111], v[166:169], v[206:209], 0
	v_mfma_f32_16x16x32_bf16 v[100:103], v[174:177], v[206:209], 0
	v_mfma_f32_16x16x32_bf16 v[92:95], v[166:169], v[214:217], 0
	v_mfma_f32_16x16x32_bf16 v[84:87], v[174:177], v[214:217], 0
	v_mfma_f32_16x16x32_bf16 v[76:79], v[166:169], v[222:225], 0
	v_mfma_f32_16x16x32_bf16 v[68:71], v[174:177], v[222:225], 0
	v_mfma_f32_16x16x32_bf16 v[124:127], v[170:173], v[202:205], v[124:127]
	v_mfma_f32_16x16x32_bf16 v[116:119], v[178:181], v[202:205], v[116:119]
	v_mfma_f32_16x16x32_bf16 v[108:111], v[170:173], v[210:213], v[108:111]
	v_mfma_f32_16x16x32_bf16 v[100:103], v[178:181], v[210:213], v[100:103]
	v_mfma_f32_16x16x32_bf16 v[92:95], v[170:173], v[218:221], v[92:95]
	v_mfma_f32_16x16x32_bf16 v[84:87], v[178:181], v[218:221], v[84:87]
	v_mfma_f32_16x16x32_bf16 v[76:79], v[170:173], v[230:233], v[76:79]
	v_mfma_f32_16x16x32_bf16 v[68:71], v[178:181], v[230:233], v[68:71]
	s_setprio 0
	s_setprio 1
	v_mfma_f32_16x16x32_bf16 v[120:123], v[182:185], v[198:201], 0
	v_mfma_f32_16x16x32_bf16 v[112:115], v[190:193], v[198:201], 0
	v_mfma_f32_16x16x32_bf16 v[104:107], v[182:185], v[206:209], 0
	v_mfma_f32_16x16x32_bf16 v[96:99], v[190:193], v[206:209], 0
	v_mfma_f32_16x16x32_bf16 v[88:91], v[182:185], v[214:217], 0
	v_mfma_f32_16x16x32_bf16 v[80:83], v[190:193], v[214:217], 0
	v_mfma_f32_16x16x32_bf16 v[72:75], v[182:185], v[222:225], 0
	v_mfma_f32_16x16x32_bf16 v[64:67], v[190:193], v[222:225], 0
	v_mfma_f32_16x16x32_bf16 v[120:123], v[186:189], v[202:205], v[120:123]
	v_mfma_f32_16x16x32_bf16 v[112:115], v[194:197], v[202:205], v[112:115]
	v_mfma_f32_16x16x32_bf16 v[104:107], v[186:189], v[210:213], v[104:107]
	v_mfma_f32_16x16x32_bf16 v[96:99], v[194:197], v[210:213], v[96:99]
	v_mfma_f32_16x16x32_bf16 v[88:91], v[186:189], v[218:221], v[88:91]
	v_mfma_f32_16x16x32_bf16 v[80:83], v[194:197], v[218:221], v[80:83]
	v_mfma_f32_16x16x32_bf16 v[72:75], v[186:189], v[230:233], v[72:75]
	v_mfma_f32_16x16x32_bf16 v[64:67], v[194:197], v[230:233], v[64:67]
	s_setprio 0
	s_barrier
; #define PG8_STAGE(bufoff, gbase, voff) do { _Pragma("unroll") for (int _i = 0; _i < 2; ++_i) \
;         { unsigned _vo = (voff)[_i]; asm volatile("" : "+v"(_vo));     \
;         __builtin_amdgcn_global_load_lds((const unsigned*)((const char*)(gbase) + _vo), (PG8_LAS unsigned*)(lds + (bufoff) + ldsw + _i * 8192), 16, 0, 0); } } while (0)
; #define PG8_LDA(dst, b, h) do { _Pragma("unroll") for (int m = 0; m < 4; ++m) _Pragma("unroll") for (int k = 0; k < 2; ++k) dst[m][k] = *(const PG8_LAS bf16x8*)(lds + PG8_SA(b, h) + aoff + m * 2048 + k * 1024); } while (0)
; #define PG8_WAIT_V(n) asm volatile("s_waitcnt vmcnt(" #n ")" ::: "memory")
; #define PG8_WAIT_L(n) asm volatile("s_waitcnt lgkmcnt(" #n ")" ::: "memory")
; #define PG8_BAR __builtin_amdgcn_s_barrier()
; #define PG8_SCHED __builtin_amdgcn_sched_barrier(0)
; template <class Epi, class Sched, bool ALIGN_EPI = false, bool SP2 = false, bool ABLK = false, bool F8 = false>
; __device__ __forceinline__ void gemm_phase(PG8_LAS unsigned char* lds, const Gemm g, const Sched& S, const Epi& E, const int wave_s) {
;     ...
;             PG8_LDA(At, 0, 1); PG8_STAGE(PG8_SB(0, 0), b2, voffB); PG8_STAGE(PG8_SB(0, 1), b2 + hstep, voffB); PG8_STAGE(PG8_SA(0, 0), a2, voffA);
;             PG8_WAIT_V(8); PG8_WAIT_L(0); PG8_BAR; PG8_MMA(1, 0, At, B0); PG8_MMA(1, 1, At, B1); PG8_BAR; PG8_SCHED;
	s_add_i32 s72, s64, s3
	ds_read_b128 v[198:201], v163 offset:16384
	ds_read_b128 v[202:205], v163 offset:17408
	ds_read_b128 v[206:209], v163 offset:18432
	ds_read_b128 v[210:213], v163 offset:19456
	ds_read_b128 v[214:217], v163 offset:20480
	ds_read_b128 v[218:221], v163 offset:21504
	ds_read_b128 v[222:225], v163 offset:22528
	ds_read_b128 v[230:233], v163 offset:23552
	s_mov_b32 m0, s72
	s_nop 0
	global_load_lds_dwordx4 v157, s[62:63]
	s_add_i32 m0, s72, 0x2000
	s_add_u32 s72, s62, 0x80000
	global_load_lds_dwordx4 v159, s[62:63]
	s_addc_u32 s73, s63, 0
	s_add_i32 s83, s65, s3
	s_mov_b32 m0, s83
	s_nop 0
	global_load_lds_dwordx4 v157, s[72:73]
	s_add_i32 m0, s83, 0x2000
	s_nop 0
	global_load_lds_dwordx4 v159, s[72:73]
	s_mov_b32 m0, s22
	s_nop 0
	global_load_lds_dwordx4 v156, s[60:61]
	s_mov_b32 m0, s23
	s_nop 0
	global_load_lds_dwordx4 v158, s[60:61]
	s_waitcnt vmcnt(8)
	s_waitcnt lgkmcnt(0)
	s_barrier
	s_setprio 1
	s_waitcnt lgkmcnt(0)
	v_mfma_f32_16x16x32_bf16 v[60:63], v[166:169], v[198:201], 0
	v_mfma_f32_16x16x32_bf16 v[52:55], v[174:177], v[198:201], 0
	v_mfma_f32_16x16x32_bf16 v[44:47], v[166:169], v[206:209], 0
	v_mfma_f32_16x16x32_bf16 v[36:39], v[174:177], v[206:209], 0
	v_mfma_f32_16x16x32_bf16 v[28:31], v[166:169], v[214:217], 0
	v_mfma_f32_16x16x32_bf16 v[20:23], v[174:177], v[214:217], 0
	v_mfma_f32_16x16x32_bf16 v[12:15], v[166:169], v[222:225], 0
	v_mfma_f32_16x16x32_bf16 v[4:7], v[174:177], v[222:225], 0
	v_mfma_f32_16x16x32_bf16 v[60:63], v[170:173], v[202:205], v[60:63]
	v_mfma_f32_16x16x32_bf16 v[52:55], v[178:181], v[202:205], v[52:55]
	v_mfma_f32_16x16x32_bf16 v[44:47], v[170:173], v[210:213], v[44:47]
	v_mfma_f32_16x16x32_bf16 v[36:39], v[178:181], v[210:213], v[36:39]
	v_mfma_f32_16x16x32_bf16 v[28:31], v[170:173], v[218:221], v[28:31]
	v_mfma_f32_16x16x32_bf16 v[20:23], v[178:181], v[218:221], v[20:23]
	v_mfma_f32_16x16x32_bf16 v[12:15], v[170:173], v[230:233], v[12:15]
	v_mfma_f32_16x16x32_bf16 v[4:7], v[178:181], v[230:233], v[4:7]
	s_setprio 0
	s_setprio 1
	v_mfma_f32_16x16x32_bf16 v[56:59], v[182:185], v[198:201], 0
	v_mfma_f32_16x16x32_bf16 v[48:51], v[190:193], v[198:201], 0
	v_mfma_f32_16x16x32_bf16 v[40:43], v[182:185], v[206:209], 0
	v_mfma_f32_16x16x32_bf16 v[32:35], v[190:193], v[206:209], 0
	v_mfma_f32_16x16x32_bf16 v[24:27], v[182:185], v[214:217], 0
	v_mfma_f32_16x16x32_bf16 v[16:19], v[190:193], v[214:217], 0
	v_mfma_f32_16x16x32_bf16 v[8:11], v[182:185], v[222:225], 0
	v_mfma_f32_16x16x32_bf16 v[0:3], v[190:193], v[222:225], 0
	v_mfma_f32_16x16x32_bf16 v[56:59], v[186:189], v[202:205], v[56:59]
	v_mfma_f32_16x16x32_bf16 v[48:51], v[194:197], v[202:205], v[48:51]
	v_mfma_f32_16x16x32_bf16 v[40:43], v[186:189], v[210:213], v[40:43]
	v_mfma_f32_16x16x32_bf16 v[32:35], v[194:197], v[210:213], v[32:35]
	v_mfma_f32_16x16x32_bf16 v[24:27], v[186:189], v[218:221], v[24:27]
	v_mfma_f32_16x16x32_bf16 v[16:19], v[194:197], v[218:221], v[16:19]
	v_mfma_f32_16x16x32_bf16 v[8:11], v[186:189], v[230:233], v[8:11]
	v_mfma_f32_16x16x32_bf16 v[0:3], v[194:197], v[230:233], v[0:3]
	s_setprio 0
	s_barrier
	s_branch .Lmid_p1

; #define PG8_STAGE(bufoff, gbase, voff) do { _Pragma("unroll") for (int _i = 0; _i < 2; ++_i) \
;         { unsigned _vo = (voff)[_i]; asm volatile("" : "+v"(_vo));     \
;         __builtin_amdgcn_global_load_lds((const unsigned*)((const char*)(gbase) + _vo), (PG8_LAS unsigned*)(lds + (bufoff) + ldsw + _i * 8192), 16, 0, 0); } } while (0)
; #define PG8_LDA(dst, b, h) do { _Pragma("unroll") for (int m = 0; m < 4; ++m) _Pragma("unroll") for (int k = 0; k < 2; ++k) dst[m][k] = *(const PG8_LAS bf16x8*)(lds + PG8_SA(b, h) + aoff + m * 2048 + k * 1024); } while (0)
; #define PG8_LDB(dst, b, h) do { _Pragma("unroll") for (int n = 0; n < 2; ++n) _Pragma("unroll") for (int k = 0; k < 2; ++k) dst[n][k] = *(const PG8_LAS bf16x8*)(lds + PG8_SB(b, h) + boff + n * 2048 + k * 1024); } while (0)
; #define PG8_WAIT_V(n) asm volatile("s_waitcnt vmcnt(" #n ")" ::: "memory")
; #define PG8_WAIT_L(n) asm volatile("s_waitcnt lgkmcnt(" #n ")" ::: "memory")
; #define PG8_BAR __builtin_amdgcn_s_barrier()
; #define PG8_SCHED __builtin_amdgcn_sched_barrier(0)
; template <class Epi, class Sched, bool ALIGN_EPI = false, bool SP2 = false, bool ABLK = false, bool F8 = false>
; __device__ __forceinline__ void gemm_phase(PG8_LAS unsigned char* lds, const Gemm g, const Sched& S, const Epi& E, const int wave_s) {
;     ...
;             PG8_LDB(B0, 1, 0); PG8_LDB(B1, 1, 1); PG8_SCHED; PG8_LDA(At, 1, 0); PG8_STAGE(PG8_SA(0, 1), a2 + hstepA, voffA);
;             PG8_WAIT_V(8); PG8_WAIT_L(0); PG8_BAR; PG8_MMA(0, 0, At, B0); PG8_MMA(0, 1, At, B1); PG8_BAR; PG8_SCHED;
;             PG8_LDA(At, 1, 1); PG8_STAGE(PG8_SB(1, 0), b3, voffB); PG8_STAGE(PG8_SB(1, 1), b3 + hstep, voffB); PG8_STAGE(PG8_SA(1, 0), a3, voffA);
;             PG8_WAIT_V(8); PG8_WAIT_L(0); PG8_BAR; PG8_MMA(1, 0, At, B0); PG8_MMA(1, 1, At, B1); PG8_BAR; PG8_SCHED;
.Lmid_p1:
	s_add_i32 s83, 0, 0x18000
	v_add_u32_e32 v128, s83, v160
	s_add_i32 s84, 0, 0x1c000
	ds_read_b128 v[166:169], v128
	ds_read_b128 v[170:173], v128 offset:1024
	ds_read_b128 v[174:177], v128 offset:2048
	ds_read_b128 v[178:181], v128 offset:3072
	v_add_u32_e32 v128, s84, v160
	ds_read_b128 v[182:185], v128
	ds_read_b128 v[186:189], v128 offset:1024
	ds_read_b128 v[190:193], v128 offset:2048
	ds_read_b128 v[194:197], v128 offset:3072
	s_add_u32 s72, s60, 0x80000
	s_mov_b32 m0, s46
	ds_read_b128 v[198:201], v163 offset:32768
	ds_read_b128 v[202:205], v163 offset:33792
	ds_read_b128 v[206:209], v163 offset:34816
	ds_read_b128 v[210:213], v163 offset:35840
	ds_read_b128 v[214:217], v163 offset:36864
	ds_read_b128 v[218:221], v163 offset:37888
	ds_read_b128 v[222:225], v163 offset:38912
	ds_read_b128 v[230:233], v163 offset:39936
	s_addc_u32 s73, s61, 0
	s_nop 0
	global_load_lds_dwordx4 v156, s[72:73]
	s_mov_b32 m0, s47
	s_nop 0
	global_load_lds_dwordx4 v158, s[72:73]
	s_waitcnt vmcnt(8)
	s_waitcnt lgkmcnt(0)
	s_barrier
	s_setprio 1
	s_waitcnt lgkmcnt(0)
	v_mfma_f32_16x16x32_bf16 v[124:127], v[166:169], v[198:201], v[124:127]
	v_mfma_f32_16x16x32_bf16 v[116:119], v[174:177], v[198:201], v[116:119]
	v_mfma_f32_16x16x32_bf16 v[108:111], v[166:169], v[206:209], v[108:111]
	v_mfma_f32_16x16x32_bf16 v[100:103], v[174:177], v[206:209], v[100:103]
	v_mfma_f32_16x16x32_bf16 v[92:95], v[166:169], v[214:217], v[92:95]
	v_mfma_f32_16x16x32_bf16 v[84:87], v[174:177], v[214:217], v[84:87]
	v_mfma_f32_16x16x32_bf16 v[76:79], v[166:169], v[222:225], v[76:79]
	v_mfma_f32_16x16x32_bf16 v[68:71], v[174:177], v[222:225], v[68:71]
	v_mfma_f32_16x16x32_bf16 v[124:127], v[170:173], v[202:205], v[124:127]
	v_mfma_f32_16x16x32_bf16 v[116:119], v[178:181], v[202:205], v[116:119]
	v_mfma_f32_16x16x32_bf16 v[108:111], v[170:173], v[210:213], v[108:111]
	v_mfma_f32_16x16x32_bf16 v[100:103], v[178:181], v[210:213], v[100:103]
	v_mfma_f32_16x16x32_bf16 v[92:95], v[170:173], v[218:221], v[92:95]
	v_mfma_f32_16x16x32_bf16 v[84:87], v[178:181], v[218:221], v[84:87]
	v_mfma_f32_16x16x32_bf16 v[76:79], v[170:173], v[230:233], v[76:79]
	v_mfma_f32_16x16x32_bf16 v[68:71], v[178:181], v[230:233], v[68:71]
	s_setprio 0
	s_setprio 1
	v_mfma_f32_16x16x32_bf16 v[120:123], v[182:185], v[198:201], v[120:123]
	v_mfma_f32_16x16x32_bf16 v[112:115], v[190:193], v[198:201], v[112:115]
	v_mfma_f32_16x16x32_bf16 v[104:107], v[182:185], v[206:209], v[104:107]
	v_mfma_f32_16x16x32_bf16 v[96:99], v[190:193], v[206:209], v[96:99]
	v_mfma_f32_16x16x32_bf16 v[88:91], v[182:185], v[214:217], v[88:91]
	v_mfma_f32_16x16x32_bf16 v[80:83], v[190:193], v[214:217], v[80:83]
	v_mfma_f32_16x16x32_bf16 v[72:75], v[182:185], v[222:225], v[72:75]
	v_mfma_f32_16x16x32_bf16 v[64:67], v[190:193], v[222:225], v[64:67]
	v_mfma_f32_16x16x32_bf16 v[120:123], v[186:189], v[202:205], v[120:123]
	v_mfma_f32_16x16x32_bf16 v[112:115], v[194:197], v[202:205], v[112:115]
	v_mfma_f32_16x16x32_bf16 v[104:107], v[186:189], v[210:213], v[104:107]
	v_mfma_f32_16x16x32_bf16 v[96:99], v[194:197], v[210:213], v[96:99]
	v_mfma_f32_16x16x32_bf16 v[88:91], v[186:189], v[218:221], v[88:91]
	v_mfma_f32_16x16x32_bf16 v[80:83], v[194:197], v[218:221], v[80:83]
	v_mfma_f32_16x16x32_bf16 v[72:75], v[186:189], v[230:233], v[72:75]
	v_mfma_f32_16x16x32_bf16 v[64:67], v[194:197], v[230:233], v[64:67]
	s_setprio 0
	s_barrier
	ds_read_b128 v[198:201], v163 offset:49152
	ds_read_b128 v[202:205], v163 offset:50176
	ds_read_b128 v[206:209], v163 offset:51200
	ds_read_b128 v[210:213], v163 offset:52224
	ds_read_b128 v[214:217], v163 offset:53248
	ds_read_b128 v[218:221], v163 offset:54272
	ds_read_b128 v[222:225], v163 offset:55296
	ds_read_b128 v[230:233], v163 offset:56320
	s_add_i32 s72, s83, s3
	s_add_u32 vcc_lo, s62, s14
	s_addc_u32 vcc_hi, s63, s15
	s_mov_b32 m0, s72
	s_nop 0
	global_load_lds_dwordx4 v157, vcc
	s_add_i32 m0, s72, 0x2000
	s_nop 0
	s_add_u32 vcc_lo, s62, s14
	s_addc_u32 vcc_hi, s63, s15
	s_add_u32 s62, s62, 0x80080
	s_addc_u32 s63, s63, 0
	s_add_i32 s72, s84, s3
	global_load_lds_dwordx4 v159, vcc
	s_mov_b32 m0, s72
	s_nop 0
	global_load_lds_dwordx4 v157, s[62:63]
	s_add_i32 m0, s72, 0x2000
	s_nop 0
	global_load_lds_dwordx4 v159, s[62:63]
	s_mov_b32 m0, s55
	s_add_u32 vcc_lo, s60, s14
	s_addc_u32 vcc_hi, s61, s15
	v_mov_b32_e32 v128, v158
	global_load_lds_dwordx4 v156, vcc
	s_mov_b32 m0, s57
	s_add_u32 vcc_lo, s60, s14
	s_addc_u32 vcc_hi, s61, s15
	global_load_lds_dwordx4 v158, vcc
	s_waitcnt vmcnt(8)
	s_waitcnt lgkmcnt(0)
	s_barrier
	s_setprio 1
	s_waitcnt lgkmcnt(0)
	v_mfma_f32_16x16x32_bf16 v[60:63], v[166:169], v[198:201], v[60:63]
	v_mfma_f32_16x16x32_bf16 v[52:55], v[174:177], v[198:201], v[52:55]
	v_mfma_f32_16x16x32_bf16 v[44:47], v[166:169], v[206:209], v[44:47]
	v_mfma_f32_16x16x32_bf16 v[36:39], v[174:177], v[206:209], v[36:39]
	v_mfma_f32_16x16x32_bf16 v[28:31], v[166:169], v[214:217], v[28:31]
	v_mfma_f32_16x16x32_bf16 v[20:23], v[174:177], v[214:217], v[20:23]
	v_mfma_f32_16x16x32_bf16 v[12:15], v[166:169], v[222:225], v[12:15]
	v_mfma_f32_16x16x32_bf16 v[4:7], v[174:177], v[222:225], v[4:7]
	v_mfma_f32_16x16x32_bf16 v[60:63], v[170:173], v[202:205], v[60:63]
	v_mfma_f32_16x16x32_bf16 v[52:55], v[178:181], v[202:205], v[52:55]
	v_mfma_f32_16x16x32_bf16 v[44:47], v[170:173], v[210:213], v[44:47]
	v_mfma_f32_16x16x32_bf16 v[36:39], v[178:181], v[210:213], v[36:39]
	v_mfma_f32_16x16x32_bf16 v[28:31], v[170:173], v[218:221], v[28:31]
	v_mfma_f32_16x16x32_bf16 v[20:23], v[178:181], v[218:221], v[20:23]
	v_mfma_f32_16x16x32_bf16 v[12:15], v[170:173], v[230:233], v[12:15]
	v_mfma_f32_16x16x32_bf16 v[4:7], v[178:181], v[230:233], v[4:7]
	s_setprio 0
	s_setprio 1
	v_mfma_f32_16x16x32_bf16 v[56:59], v[182:185], v[198:201], v[56:59]
	v_mfma_f32_16x16x32_bf16 v[48:51], v[190:193], v[198:201], v[48:51]
	v_mfma_f32_16x16x32_bf16 v[40:43], v[182:185], v[206:209], v[40:43]
	v_mfma_f32_16x16x32_bf16 v[32:35], v[190:193], v[206:209], v[32:35]
	v_mfma_f32_16x16x32_bf16 v[24:27], v[182:185], v[214:217], v[24:27]
	v_mfma_f32_16x16x32_bf16 v[16:19], v[190:193], v[214:217], v[16:19]
	v_mfma_f32_16x16x32_bf16 v[8:11], v[182:185], v[222:225], v[8:11]
	v_mfma_f32_16x16x32_bf16 v[0:3], v[190:193], v[222:225], v[0:3]
	v_mfma_f32_16x16x32_bf16 v[56:59], v[186:189], v[202:205], v[56:59]
	v_mfma_f32_16x16x32_bf16 v[48:51], v[194:197], v[202:205], v[48:51]
	v_mfma_f32_16x16x32_bf16 v[40:43], v[186:189], v[210:213], v[40:43]
	v_mfma_f32_16x16x32_bf16 v[32:35], v[194:197], v[210:213], v[32:35]
	v_mfma_f32_16x16x32_bf16 v[24:27], v[186:189], v[218:221], v[24:27]
	v_mfma_f32_16x16x32_bf16 v[16:19], v[194:197], v[218:221], v[16:19]
	v_mfma_f32_16x16x32_bf16 v[8:11], v[186:189], v[230:233], v[8:11]
	v_mfma_f32_16x16x32_bf16 v[0:3], v[194:197], v[230:233], v[0:3]
	s_setprio 0
	s_barrier
	s_add_i32 s81, s81, 2
	s_add_u32 s58, s58, 0x100
	s_addc_u32 s59, s59, 0
	s_add_u32 s79, s79, 0x100
	s_addc_u32 s80, s80, 0
	s_cmp_gt_u32 s81, 29
	s_cbranch_scc1 .LBB0_226

;     __device__ bool next(int i, Unit& u) const { const bool r = base.next(i >> 1, u); u.kh = i & 1; return r; }
; #define PG8_STAGE(bufoff, gbase, voff) do { _Pragma("unroll") for (int _i = 0; _i < 2; ++_i) \
;         { unsigned _vo = (voff)[_i]; asm volatile("" : "+v"(_vo));     \
;         __builtin_amdgcn_global_load_lds((const unsigned*)((const char*)(gbase) + _vo), (PG8_LAS unsigned*)(lds + (bufoff) + ldsw + _i * 8192), 16, 0, 0); } } while (0)
; #define PG8_LDA(dst, b, h) do { _Pragma("unroll") for (int m = 0; m < 4; ++m) _Pragma("unroll") for (int k = 0; k < 2; ++k) dst[m][k] = *(const PG8_LAS bf16x8*)(lds + PG8_SA(b, h) + aoff + m * 2048 + k * 1024); } while (0)
; #define PG8_WAIT_V(n) asm volatile("s_waitcnt vmcnt(" #n ")" ::: "memory")
; #define PG8_WAIT_L(n) asm volatile("s_waitcnt lgkmcnt(" #n ")" ::: "memory")
; template <class Epi, class Sched, bool ALIGN_EPI = false, bool SP2 = false, bool ABLK = false, bool F8 = false>
; __device__ __forceinline__ void gemm_phase(PG8_LAS unsigned char* lds, const Gemm g, const Sched& S, const Epi& E, const int wave_s) {
;     ...
;         const bool has_next = S.next(ui + 1, nxt); nxt.par = (ui + 1) & 1;
;         const char* nA = has_next ? (const char*)g.A + (size_t)nxt.pm * tstep + nxt.kh * khbA : cA; const char* nB = has_next ? (const char*)g.Bt + (size_t)nxt.pn * tstep + nxt.kh * khb : cB;
;         for (int t = 0; t < nt; t += 2) {
;             const bool last = (t == nt - 2);
;             const char* a1 = cA + (size_t)(t + 1) * kstepA;
;             const char* a2 = last ? nA : cA + (size_t)(t + 2) * kstepA; const char* b2 = last ? nB : cB + (size_t)(t + 2) * kstep;
;             const char* a3 = a2 + kstepA; const char* b3 = b2 + kstep;
;             if (last && has_next) { S.a_ready(nxt); if constexpr (Epi::PREF) E.prefetch(nxt, wid, lane); }
;             if constexpr (SP2) {
;             PG8_LDB(B0, 0, 0); PG8_LDB(B1, 0, 1); PG8_SCHED; PG8_LDA(At, 0, 0); PG8_STAGE(PG8_SA(1, 1), a1 + hstepA, voffA);
;             PG8_WAIT_V(8); PG8_WAIT_L(0); PG8_BAR; PG8_MMA(0, 0, At, B0); PG8_MMA(0, 1, At, B1); PG8_BAR; PG8_SCHED;
;             PG8_LDA(At, 0, 1); PG8_STAGE(PG8_SB(0, 0), b2, voffB); PG8_STAGE(PG8_SB(0, 1), b2 + hstep, voffB); PG8_STAGE(PG8_SA(0, 0), a2, voffA);
;             PG8_WAIT_V(8); PG8_WAIT_L(0); PG8_BAR; PG8_MMA(1, 0, At, B0); PG8_MMA(1, 1, At, B1); PG8_BAR; PG8_SCHED;
.LBB0_809:
	s_ashr_i32 s43, s42, 31
	s_and_b32 s64, s63, 1
	s_lshl_b64 s[46:47], s[42:43], 19
	s_add_u32 s46, s38, s46
	s_addc_u32 s47, s39, s47
	s_and_b64 s[48:49], exec, s[10:11]
	s_cselect_b32 s43, s55, s47
	s_cselect_b32 s66, s54, s46
	s_ashr_i32 s41, s40, 31
	s_lshl_b64 s[48:49], s[40:41], 19
	s_add_u32 s48, s18, s48
	s_addc_u32 s49, s19, s49
	s_and_b64 s[58:59], exec, s[10:11]
	s_cselect_b32 s41, s57, s49
	s_cselect_b32 s67, s56, s48
	s_lshl_b32 s58, s42, 8
	s_ashr_i32 s59, s58, 31
	s_lshl_b32 s75, s64, 10
	s_or_b64 s[10:11], s[44:45], s[10:11]
	s_add_u32 s54, s54, 0x40080
	s_addc_u32 s55, s55, 0
	s_add_u32 s72, s56, 0x100
	v_lshl_add_u64 v[228:229], s[58:59], 2, v[130:131]
	s_addc_u32 s73, s57, 0
	s_mov_b32 s74, -2
	s_add_i32 s75, s95, s75
	s_mov_b64 s[56:57], -1
	v_add_u32_e32 v128, s61, v142
	ds_read_b128 v[148:151], v128
	ds_read_b128 v[152:155], v128 offset:1024
	ds_read_b128 v[156:159], v128 offset:2048
	ds_read_b128 v[160:163], v128 offset:3072
	v_add_u32_e32 v128, s62, v142
	ds_read_b128 v[164:167], v128
	ds_read_b128 v[168:171], v128 offset:1024
	ds_read_b128 v[172:175], v128 offset:2048
	ds_read_b128 v[176:179], v128 offset:3072
	s_add_u32 s58, s54, 0xfffc0080
	s_addc_u32 s59, s55, -1
	s_and_b64 s[56:57], s[56:57], exec
	s_cselect_b32 s57, s59, s43
	s_cselect_b32 s56, s58, s66
	s_cselect_b32 s59, s73, s41
	s_cselect_b32 s58, s72, s67
	ds_read_b128 v[180:183], v143
	ds_read_b128 v[184:187], v143 offset:1024
	ds_read_b128 v[188:191], v143 offset:2048
	ds_read_b128 v[192:195], v143 offset:3072
	ds_read_b128 v[196:199], v143 offset:4096
	ds_read_b128 v[200:203], v143 offset:5120
	ds_read_b128 v[204:207], v143 offset:6144
	ds_read_b128 v[208:211], v143 offset:7168
	s_add_i32 m0, s20, 0xc000
	s_nop 0
	global_load_lds_dwordx4 v147, s[54:55]
	s_add_i32 m0, s20, 0xe000
	s_nop 0
	global_load_lds_dwordx4 v140, s[54:55]
	s_waitcnt vmcnt(8)
	s_waitcnt lgkmcnt(0)
	s_barrier
	s_setprio 1
	s_waitcnt lgkmcnt(0)
	v_mfma_f32_16x16x128_f8f6f4 v[124:127], v[148:155], v[180:187], 0
	v_mfma_f32_16x16x128_f8f6f4 v[116:119], v[156:163], v[180:187], 0
	v_mfma_f32_16x16x128_f8f6f4 v[108:111], v[148:155], v[188:195], 0
	v_mfma_f32_16x16x128_f8f6f4 v[100:103], v[156:163], v[188:195], 0
	v_mfma_f32_16x16x128_f8f6f4 v[212:215], v[148:155], v[196:203], 0
	v_mfma_f32_16x16x128_f8f6f4 v[216:219], v[156:163], v[196:203], 0
	v_mfma_f32_16x16x128_f8f6f4 v[220:223], v[148:155], v[204:211], 0
	v_mfma_f32_16x16x128_f8f6f4 v[224:227], v[156:163], v[204:211], 0
	s_setprio 0
	s_setprio 1
	v_mfma_f32_16x16x128_f8f6f4 v[120:123], v[164:171], v[180:187], 0
	v_mfma_f32_16x16x128_f8f6f4 v[112:115], v[172:179], v[180:187], 0
	v_mfma_f32_16x16x128_f8f6f4 v[104:107], v[164:171], v[188:195], 0
	v_mfma_f32_16x16x128_f8f6f4 v[96:99], v[172:179], v[188:195], 0
	v_mfma_f32_16x16x128_f8f6f4 v[180:183], v[164:171], v[196:203], 0
	v_mfma_f32_16x16x128_f8f6f4 v[184:187], v[172:179], v[196:203], 0
	v_mfma_f32_16x16x128_f8f6f4 v[188:191], v[164:171], v[204:211], 0
	v_mfma_f32_16x16x128_f8f6f4 v[192:195], v[172:179], v[204:211], 0
	s_setprio 0
	s_barrier
	s_add_i32 s76, s61, s3
	s_nop 2
	ds_read_b128 v[64:67], v143 offset:16384
	ds_read_b128 v[68:71], v143 offset:17408
	ds_read_b128 v[72:75], v143 offset:18432
	ds_read_b128 v[76:79], v143 offset:19456
	ds_read_b128 v[80:83], v143 offset:20480
	ds_read_b128 v[84:87], v143 offset:21504
	ds_read_b128 v[88:91], v143 offset:22528
	ds_read_b128 v[92:95], v143 offset:23552
	s_mov_b32 m0, s76
	s_nop 0
	global_load_lds_dwordx4 v254, s[58:59]
	s_add_i32 m0, s76, 0x2000
	s_add_u32 s76, s58, 0x40000
	global_load_lds_dwordx4 v141, s[58:59]
	s_addc_u32 s77, s59, 0
	s_add_i32 s78, s62, s3
	s_mov_b32 m0, s78
	s_nop 0
	global_load_lds_dwordx4 v254, s[76:77]
	s_add_i32 m0, s78, 0x2000
	s_nop 0
	global_load_lds_dwordx4 v141, s[76:77]
	s_mov_b32 m0, s20
	s_nop 0
	global_load_lds_dwordx4 v147, s[56:57]
	s_mov_b32 m0, s21
	s_nop 0
	global_load_lds_dwordx4 v140, s[56:57]
	s_waitcnt vmcnt(8)
	s_waitcnt lgkmcnt(0)
	s_barrier
	s_setprio 1
	s_waitcnt lgkmcnt(0)
	v_mfma_f32_16x16x128_f8f6f4 v[60:63], v[148:155], v[64:71], 0
	v_mfma_f32_16x16x128_f8f6f4 v[52:55], v[156:163], v[64:71], 0
	v_mfma_f32_16x16x128_f8f6f4 v[44:47], v[148:155], v[72:79], 0
	v_mfma_f32_16x16x128_f8f6f4 v[204:207], v[156:163], v[72:79], 0
	v_mfma_f32_16x16x128_f8f6f4 v[208:211], v[148:155], v[80:87], 0
	v_mfma_f32_16x16x128_f8f6f4 v[230:233], v[156:163], v[80:87], 0
	v_mfma_f32_16x16x128_f8f6f4 v[234:237], v[148:155], v[88:95], 0
	v_mfma_f32_16x16x128_f8f6f4 v[238:241], v[156:163], v[88:95], 0
	s_setprio 0
	s_setprio 1
	v_mfma_f32_16x16x128_f8f6f4 v[56:59], v[164:171], v[64:71], 0
	v_mfma_f32_16x16x128_f8f6f4 v[48:51], v[172:179], v[64:71], 0
	v_mfma_f32_16x16x128_f8f6f4 v[40:43], v[164:171], v[72:79], 0
	v_mfma_f32_16x16x128_f8f6f4 v[242:245], v[172:179], v[72:79], 0
	v_mfma_f32_16x16x128_f8f6f4 v[246:249], v[164:171], v[80:87], 0
	v_mfma_f32_16x16x128_f8f6f4 v[250:253], v[172:179], v[80:87], 0
	v_mfma_f32_16x16x128_f8f6f4 v[132:135], v[164:171], v[88:95], 0
	v_mfma_f32_16x16x128_f8f6f4 v[136:139], v[172:179], v[88:95], 0
	s_setprio 0
	s_barrier
	s_branch .Lmid_p7

; #define PG8_STAGE(bufoff, gbase, voff) do { _Pragma("unroll") for (int _i = 0; _i < 2; ++_i) \
;         { unsigned _vo = (voff)[_i]; asm volatile("" : "+v"(_vo));     \
;         __builtin_amdgcn_global_load_lds((const unsigned*)((const char*)(gbase) + _vo), (PG8_LAS unsigned*)(lds + (bufoff) + ldsw + _i * 8192), 16, 0, 0); } } while (0)
; #define PG8_LDA(dst, b, h) do { _Pragma("unroll") for (int m = 0; m < 4; ++m) _Pragma("unroll") for (int k = 0; k < 2; ++k) dst[m][k] = *(const PG8_LAS bf16x8*)(lds + PG8_SA(b, h) + aoff + m * 2048 + k * 1024); } while (0)
; #define PG8_LDB(dst, b, h) do { _Pragma("unroll") for (int n = 0; n < 2; ++n) _Pragma("unroll") for (int k = 0; k < 2; ++k) dst[n][k] = *(const PG8_LAS bf16x8*)(lds + PG8_SB(b, h) + boff + n * 2048 + k * 1024); } while (0)
; #define PG8_WAIT_V(n) asm volatile("s_waitcnt vmcnt(" #n ")" ::: "memory")
; #define PG8_WAIT_L(n) asm volatile("s_waitcnt lgkmcnt(" #n ")" ::: "memory")
; #define PG8_BAR __builtin_amdgcn_s_barrier()
; #define PG8_SCHED __builtin_amdgcn_sched_barrier(0)
; template <class Epi, class Sched, bool ALIGN_EPI = false, bool SP2 = false, bool ABLK = false, bool F8 = false>
; __device__ __forceinline__ void gemm_phase(PG8_LAS unsigned char* lds, const Gemm g, const Sched& S, const Epi& E, const int wave_s) {
;     ...
;             PG8_LDB(B0, 1, 0); PG8_LDB(B1, 1, 1); PG8_SCHED; PG8_LDA(At, 1, 0); PG8_STAGE(PG8_SA(0, 1), a2 + hstepA, voffA);
;             PG8_WAIT_V(8); PG8_WAIT_L(0); PG8_BAR; PG8_MMA(0, 0, At, B0); PG8_MMA(0, 1, At, B1); PG8_BAR; PG8_SCHED;
;             PG8_LDA(At, 1, 1); PG8_STAGE(PG8_SB(1, 0), b3, voffB); PG8_STAGE(PG8_SB(1, 1), b3 + hstep, voffB); PG8_STAGE(PG8_SA(1, 0), a3, voffA);
;             PG8_WAIT_V(8); PG8_WAIT_L(0); PG8_BAR; PG8_MMA(1, 0, At, B0); PG8_MMA(1, 1, At, B1); PG8_BAR; PG8_SCHED;
.Lmid_p7:
	s_add_i32 s78, 0, 0x18000
	s_nop 2
	v_add_u32_e32 v8, s78, v142
	s_add_i32 s79, 0, 0x1c000
	ds_read_b128 v[0:3], v8
	ds_read_b128 v[4:7], v8 offset:1024
	ds_read_b128 v[148:151], v8 offset:2048
	ds_read_b128 v[152:155], v8 offset:3072
	v_add_u32_e32 v8, s79, v142
	ds_read_b128 v[156:159], v8
	ds_read_b128 v[160:163], v8 offset:1024
	ds_read_b128 v[164:167], v8 offset:2048
	ds_read_b128 v[168:171], v8 offset:3072
	s_add_u32 s76, s56, 0x40000
	s_mov_b32 m0, s22
	ds_read_b128 v[8:11], v143 offset:32768
	ds_read_b128 v[12:15], v143 offset:33792
	ds_read_b128 v[16:19], v143 offset:34816
	ds_read_b128 v[20:23], v143 offset:35840
	ds_read_b128 v[24:27], v143 offset:36864
	ds_read_b128 v[28:31], v143 offset:37888
	ds_read_b128 v[32:35], v143 offset:38912
	ds_read_b128 v[36:39], v143 offset:39936
	s_addc_u32 s77, s57, 0
	s_nop 0
	global_load_lds_dwordx4 v147, s[76:77]
	s_mov_b32 m0, s23
	s_nop 0
	global_load_lds_dwordx4 v140, s[76:77]
	s_waitcnt vmcnt(8)
	s_waitcnt lgkmcnt(0)
	s_barrier
	s_setprio 1
	s_waitcnt lgkmcnt(0)
	v_mfma_f32_16x16x128_f8f6f4 v[124:127], v[0:7], v[8:15], v[124:127]
	v_mfma_f32_16x16x128_f8f6f4 v[116:119], v[148:155], v[8:15], v[116:119]
	v_mfma_f32_16x16x128_f8f6f4 v[108:111], v[0:7], v[16:23], v[108:111]
	v_mfma_f32_16x16x128_f8f6f4 v[100:103], v[148:155], v[16:23], v[100:103]
	v_mfma_f32_16x16x128_f8f6f4 v[92:95], v[0:7], v[24:31], v[212:215]
	v_mfma_f32_16x16x128_f8f6f4 v[84:87], v[148:155], v[24:31], v[216:219]
	v_mfma_f32_16x16x128_f8f6f4 v[76:79], v[0:7], v[32:39], v[220:223]
	v_mfma_f32_16x16x128_f8f6f4 v[68:71], v[148:155], v[32:39], v[224:227]
	s_setprio 0
	s_setprio 1
	v_mfma_f32_16x16x128_f8f6f4 v[120:123], v[156:163], v[8:15], v[120:123]
	v_mfma_f32_16x16x128_f8f6f4 v[112:115], v[164:171], v[8:15], v[112:115]
	v_mfma_f32_16x16x128_f8f6f4 v[104:107], v[156:163], v[16:23], v[104:107]
	v_mfma_f32_16x16x128_f8f6f4 v[96:99], v[164:171], v[16:23], v[96:99]
	v_mfma_f32_16x16x128_f8f6f4 v[88:91], v[156:163], v[24:31], v[180:183]
	v_mfma_f32_16x16x128_f8f6f4 v[80:83], v[164:171], v[24:31], v[184:187]
	v_mfma_f32_16x16x128_f8f6f4 v[72:75], v[156:163], v[32:39], v[188:191]
	v_mfma_f32_16x16x128_f8f6f4 v[64:67], v[164:171], v[32:39], v[192:195]
	s_setprio 0
	s_barrier
	ds_read_b128 v[172:175], v143 offset:49152
	ds_read_b128 v[176:179], v143 offset:50176
	ds_read_b128 v[180:183], v143 offset:51200
	ds_read_b128 v[184:187], v143 offset:52224
	ds_read_b128 v[188:191], v143 offset:53248
	ds_read_b128 v[192:195], v143 offset:54272
	ds_read_b128 v[196:199], v143 offset:55296
	ds_read_b128 v[200:203], v143 offset:56320
	s_add_i32 s76, s78, s3
	s_add_u32 vcc_lo, s58, s12
	s_addc_u32 vcc_hi, s59, s13
	s_mov_b32 m0, s76
	s_nop 0
	global_load_lds_dwordx4 v254, vcc
	s_add_i32 m0, s76, 0x2000
	s_add_u32 vcc_lo, s58, s12
	s_addc_u32 vcc_hi, s59, s13
	s_add_u32 s58, s58, 0x40080
	global_load_lds_dwordx4 v141, vcc
	s_addc_u32 s59, s59, 0
	s_add_i32 s76, s79, s3
	s_mov_b32 m0, s76
	s_nop 0
	global_load_lds_dwordx4 v254, s[58:59]
	s_add_i32 m0, s76, 0x2000
	s_nop 0
	global_load_lds_dwordx4 v141, s[58:59]
	s_mov_b32 m0, s33
	s_add_u32 vcc_lo, s56, s12
	s_addc_u32 vcc_hi, s57, s13
	v_mov_b32_e32 v128, v140
	global_load_lds_dwordx4 v147, vcc
	s_mov_b32 m0, s51
	s_add_u32 vcc_lo, s56, s12
	s_addc_u32 vcc_hi, s57, s13
	global_load_lds_dwordx4 v140, vcc
	s_waitcnt vmcnt(8)
	s_waitcnt lgkmcnt(0)
	s_barrier
	s_setprio 1
	s_waitcnt lgkmcnt(0)
	v_mfma_f32_16x16x128_f8f6f4 v[60:63], v[0:7], v[172:179], v[60:63]
	v_mfma_f32_16x16x128_f8f6f4 v[52:55], v[148:155], v[172:179], v[52:55]
	v_mfma_f32_16x16x128_f8f6f4 v[44:47], v[0:7], v[180:187], v[44:47]
	v_mfma_f32_16x16x128_f8f6f4 v[36:39], v[148:155], v[180:187], v[204:207]
	v_mfma_f32_16x16x128_f8f6f4 v[28:31], v[0:7], v[188:195], v[208:211]
	v_mfma_f32_16x16x128_f8f6f4 v[20:23], v[148:155], v[188:195], v[230:233]
	v_mfma_f32_16x16x128_f8f6f4 v[12:15], v[0:7], v[196:203], v[234:237]
	v_mfma_f32_16x16x128_f8f6f4 v[4:7], v[148:155], v[196:203], v[238:241]
	s_setprio 0
	s_setprio 1
	v_mfma_f32_16x16x128_f8f6f4 v[56:59], v[156:163], v[172:179], v[56:59]
	v_mfma_f32_16x16x128_f8f6f4 v[48:51], v[164:171], v[172:179], v[48:51]
	v_mfma_f32_16x16x128_f8f6f4 v[40:43], v[156:163], v[180:187], v[40:43]
	v_mfma_f32_16x16x128_f8f6f4 v[32:35], v[164:171], v[180:187], v[242:245]
	v_mfma_f32_16x16x128_f8f6f4 v[24:27], v[156:163], v[188:195], v[246:249]
	v_mfma_f32_16x16x128_f8f6f4 v[16:19], v[164:171], v[188:195], v[250:253]
	v_mfma_f32_16x16x128_f8f6f4 v[8:11], v[156:163], v[196:203], v[132:135]
	v_mfma_f32_16x16x128_f8f6f4 v[0:3], v[164:171], v[196:203], v[136:139]
	s_setprio 0
	s_barrier
	s_add_i32 s74, s74, 2
	s_add_u32 s54, s54, 0x100
	s_addc_u32 s55, s55, 0
	s_add_u32 s72, s72, 0x100
	s_addc_u32 s73, s73, 0
	s_cmp_gt_u32 s74, 13
	s_cbranch_scc1 .LBB0_813
